# v28: v27 + softmax-shift max|rpb| loads batched (2 round trips instead of 60 serial)
# baseline (speedup 1.0000x reference)
.LBB0_86:
	s_or_b64 exec, exec, s[4:5]
	s_cmpk_eq_i32 s2, 0xff
	s_cselect_b64 s[4:5], -1, 0
	s_cmp_eq_u32 s3, 7
	s_cselect_b64 s[6:7], -1, 0
	s_and_b64 s[4:5], s[4:5], s[6:7]
	s_and_b64 vcc, exec, s[4:5]
	s_cbranch_vccz .LBB0_100
	v_lshlrev_b32_e32 v0, 2, v102
	global_load_dword v5, v0, s[10:11]
	global_load_dword v4, v0, s[12:13]
	v_lshlrev_b32_e32 v2, 4, v102
	v_mov_b32_e32 v1, 0
	s_mov_b32 s4, s14
	s_mov_b32 s5, s15
	global_load_dwordx4 v[16:19], v2, s[4:5] offset:0
	global_load_dwordx4 v[20:23], v2, s[4:5] offset:1024
	global_load_dwordx4 v[24:27], v2, s[4:5] offset:2048
	global_load_dwordx4 v[28:31], v2, s[4:5] offset:3072
	s_add_u32 s4, s4, 0x1000
	s_addc_u32 s5, s5, 0
	global_load_dwordx4 v[32:35], v2, s[4:5] offset:0
	global_load_dwordx4 v[36:39], v2, s[4:5] offset:1024
	global_load_dwordx4 v[40:43], v2, s[4:5] offset:2048
	global_load_dwordx4 v[44:47], v2, s[4:5] offset:3072
	s_add_u32 s4, s4, 0x1000
	s_addc_u32 s5, s5, 0
	global_load_dwordx4 v[48:51], v2, s[4:5] offset:0
	global_load_dwordx4 v[52:55], v2, s[4:5] offset:1024
	global_load_dwordx4 v[56:59], v2, s[4:5] offset:2048
	global_load_dwordx4 v[60:63], v2, s[4:5] offset:3072
	s_add_u32 s4, s4, 0x1000
	s_addc_u32 s5, s5, 0
	global_load_dwordx4 v[64:67], v2, s[4:5] offset:0
	global_load_dwordx4 v[68:71], v2, s[4:5] offset:1024
	global_load_dwordx4 v[72:75], v2, s[4:5] offset:2048
	global_load_dwordx4 v[76:79], v2, s[4:5] offset:3072
	s_add_u32 s4, s4, 0x1000
	s_addc_u32 s5, s5, 0
	s_waitcnt vmcnt(0)
	v_max3_f32 v1, v1, |v16|, |v17|
	v_max3_f32 v1, v1, |v18|, |v19|
	v_max3_f32 v1, v1, |v20|, |v21|
	v_max3_f32 v1, v1, |v22|, |v23|
	v_max3_f32 v1, v1, |v24|, |v25|
	v_max3_f32 v1, v1, |v26|, |v27|
	v_max3_f32 v1, v1, |v28|, |v29|
	v_max3_f32 v1, v1, |v30|, |v31|
	v_max3_f32 v1, v1, |v32|, |v33|
	v_max3_f32 v1, v1, |v34|, |v35|
	v_max3_f32 v1, v1, |v36|, |v37|
	v_max3_f32 v1, v1, |v38|, |v39|
	v_max3_f32 v1, v1, |v40|, |v41|
	v_max3_f32 v1, v1, |v42|, |v43|
	v_max3_f32 v1, v1, |v44|, |v45|
	v_max3_f32 v1, v1, |v46|, |v47|
	v_max3_f32 v1, v1, |v48|, |v49|
	v_max3_f32 v1, v1, |v50|, |v51|
	v_max3_f32 v1, v1, |v52|, |v53|
	v_max3_f32 v1, v1, |v54|, |v55|
	v_max3_f32 v1, v1, |v56|, |v57|
	v_max3_f32 v1, v1, |v58|, |v59|
	v_max3_f32 v1, v1, |v60|, |v61|
	v_max3_f32 v1, v1, |v62|, |v63|
	v_max3_f32 v1, v1, |v64|, |v65|
	v_max3_f32 v1, v1, |v66|, |v67|
	v_max3_f32 v1, v1, |v68|, |v69|
	v_max3_f32 v1, v1, |v70|, |v71|
	v_max3_f32 v1, v1, |v72|, |v73|
	v_max3_f32 v1, v1, |v74|, |v75|
	v_max3_f32 v1, v1, |v76|, |v77|
	v_max3_f32 v1, v1, |v78|, |v79|
	global_load_dwordx4 v[16:19], v2, s[4:5] offset:0
	global_load_dwordx4 v[20:23], v2, s[4:5] offset:1024
	global_load_dwordx4 v[24:27], v2, s[4:5] offset:2048
	global_load_dwordx4 v[28:31], v2, s[4:5] offset:3072
	s_add_u32 s4, s4, 0x1000
	s_addc_u32 s5, s5, 0
	global_load_dwordx4 v[32:35], v2, s[4:5] offset:0
	global_load_dwordx4 v[36:39], v2, s[4:5] offset:1024
	global_load_dwordx4 v[40:43], v2, s[4:5] offset:2048
	global_load_dwordx4 v[44:47], v2, s[4:5] offset:3072
	s_add_u32 s4, s4, 0x1000
	s_addc_u32 s5, s5, 0
	global_load_dwordx4 v[48:51], v2, s[4:5] offset:0
	global_load_dwordx4 v[52:55], v2, s[4:5] offset:1024
	global_load_dwordx4 v[56:59], v2, s[4:5] offset:2048
	global_load_dwordx4 v[60:63], v2, s[4:5] offset:3072
	s_add_u32 s4, s4, 0x1000
	s_addc_u32 s5, s5, 0
	global_load_dwordx4 v[64:67], v2, s[4:5] offset:0
	v_mov_b32_e32 v68, 0
	v_mov_b32_e32 v69, 0
	v_mov_b32_e32 v70, 0
	v_mov_b32_e32 v71, 0
	s_mov_b64 s[6:7], exec
	s_mov_b64 exec, 15
	global_load_dwordx4 v[68:71], v2, s[4:5] offset:1024
	s_mov_b64 exec, s[6:7]
	s_waitcnt vmcnt(0)
	v_max3_f32 v1, v1, |v16|, |v17|
	v_max3_f32 v1, v1, |v18|, |v19|
	v_max3_f32 v1, v1, |v20|, |v21|
	v_max3_f32 v1, v1, |v22|, |v23|
	v_max3_f32 v1, v1, |v24|, |v25|
	v_max3_f32 v1, v1, |v26|, |v27|
	v_max3_f32 v1, v1, |v28|, |v29|
	v_max3_f32 v1, v1, |v30|, |v31|
	v_max3_f32 v1, v1, |v32|, |v33|
	v_max3_f32 v1, v1, |v34|, |v35|
	v_max3_f32 v1, v1, |v36|, |v37|
	v_max3_f32 v1, v1, |v38|, |v39|
	v_max3_f32 v1, v1, |v40|, |v41|
	v_max3_f32 v1, v1, |v42|, |v43|
	v_max3_f32 v1, v1, |v44|, |v45|
	v_max3_f32 v1, v1, |v46|, |v47|
	v_max3_f32 v1, v1, |v48|, |v49|
	v_max3_f32 v1, v1, |v50|, |v51|
	v_max3_f32 v1, v1, |v52|, |v53|
	v_max3_f32 v1, v1, |v54|, |v55|
	v_max3_f32 v1, v1, |v56|, |v57|
	v_max3_f32 v1, v1, |v58|, |v59|
	v_max3_f32 v1, v1, |v60|, |v61|
	v_max3_f32 v1, v1, |v62|, |v63|
	v_max3_f32 v1, v1, |v64|, |v65|
	v_max3_f32 v1, v1, |v66|, |v67|
	v_max3_f32 v1, v1, |v68|, |v69|
	v_max3_f32 v1, v1, |v70|, |v71|
	v_and_b32_e32 v0, 0x7fffffff, v5
	ds_bpermute_b32 v0, v109, v0
	v_and_b32_e32 v2, 0x7fffffff, v4
	ds_bpermute_b32 v2, v109, v2
	v_max_f32_e64 v3, |v5|, |v5|
	ds_bpermute_b32 v5, v109, v1
	s_waitcnt lgkmcnt(2)
	v_max_f32_e32 v0, v0, v0
	v_max_f32_e32 v0, v3, v0
	s_waitcnt lgkmcnt(1)
	v_max_f32_e32 v2, v2, v2
	v_max_f32_e64 v3, |v4|, |v4|
	v_max_f32_e32 v2, v3, v2
	ds_bpermute_b32 v3, v108, v0
	s_waitcnt lgkmcnt(1)
	v_max_f32_e32 v4, v5, v5
	v_max_f32_e32 v1, v1, v1
	ds_bpermute_b32 v5, v108, v2
	v_max_f32_e32 v1, v1, v4
	ds_bpermute_b32 v4, v108, v1
	s_waitcnt lgkmcnt(2)
	v_max_f32_e32 v3, v3, v3
	v_max_f32_e32 v0, v0, v3
	s_waitcnt lgkmcnt(1)
	v_max_f32_e32 v3, v5, v5
	ds_bpermute_b32 v5, v107, v0
	v_max_f32_e32 v2, v2, v3
	s_waitcnt lgkmcnt(1)
	v_max_f32_e32 v3, v4, v4
	ds_bpermute_b32 v4, v107, v2
	v_max_f32_e32 v1, v1, v3
	s_waitcnt lgkmcnt(1)
	v_max_f32_e32 v3, v5, v5
	ds_bpermute_b32 v5, v107, v1
	v_max_f32_e32 v0, v0, v3
	s_waitcnt lgkmcnt(1)
	v_max_f32_e32 v3, v4, v4
	ds_bpermute_b32 v4, v106, v0
	v_max_f32_e32 v2, v2, v3
	s_waitcnt lgkmcnt(1)
	v_max_f32_e32 v3, v5, v5
	ds_bpermute_b32 v5, v106, v2
	v_max_f32_e32 v1, v1, v3
	s_waitcnt lgkmcnt(1)
	v_max_f32_e32 v3, v4, v4
	ds_bpermute_b32 v4, v106, v1
	v_max_f32_e32 v0, v0, v3
	s_waitcnt lgkmcnt(1)
	v_max_f32_e32 v3, v5, v5
	v_max_f32_e32 v2, v2, v3
	ds_bpermute_b32 v3, v105, v0
	s_waitcnt lgkmcnt(1)
	v_max_f32_e32 v4, v4, v4
	ds_bpermute_b32 v5, v105, v2
	v_max_f32_e32 v4, v1, v4
	ds_bpermute_b32 v6, v105, v4
	s_waitcnt lgkmcnt(2)
	v_max_f32_e32 v1, v3, v3
	v_max_f32_e32 v0, v0, v1
	s_waitcnt lgkmcnt(1)
	v_max_f32_e32 v1, v5, v5
	v_max_f32_e32 v1, v2, v1
	s_waitcnt lgkmcnt(0)
	v_max_f32_e32 v2, v6, v6
	v_max_f32_e32 v3, v4, v2
	ds_bpermute_b32 v2, v104, v0
	ds_bpermute_b32 v4, v104, v1
	ds_bpermute_b32 v5, v104, v3
	v_cmp_eq_u32_e32 vcc, 0, v102
	s_and_saveexec_b64 s[4:5], vcc
	s_cbranch_execz .LBB0_99
	s_waitcnt lgkmcnt(2)
	v_max_f32_e32 v2, v2, v2
	v_max_f32_e32 v0, v0, v0
	s_waitcnt lgkmcnt(0)
	v_max_f32_e32 v5, v5, v5
	v_max_f32_e32 v3, v3, v3
	v_max_f32_e32 v4, v4, v4
	v_max_f32_e32 v1, v1, v1
	v_max_f32_e32 v0, v0, v2
	v_max_f32_e32 v3, v3, v5
	v_max_f32_e32 v1, v1, v4
	v_mul_f32_e32 v0, 0x4103d70a, v0
	v_fmac_f32_e32 v3, v1, v0
	v_mov_b32_e32 v0, 0x280000
	global_store_dword v0, v3, s[38:39]
